# XCC-aware grid barrier: poll interval s_sleep 3 instead of 8 in the hierarchical wait
# baseline (speedup 1.0000x reference)
; #define RUNPH(k, call) for (int rep_ = 0; rep_ < (((REPMASK) >> (k)) & 1) + 1; ++rep_) { call; grid.sync(); }
; __global__ void __launch_bounds__(NTH, 2) mega_kernel(Params p) {
;     ...
;   RUNPH(3, phase3(p, smem))
.Lgs3_poll:
	global_load_dword v2, v0, s[6:7] offset:136 sc1
	s_waitcnt vmcnt(0)
	v_cmp_gt_u32_e32 vcc, s10, v2
	s_cbranch_vccz .Lgs3_done
	s_sleep 3
	s_sub_u32 s11, s11, 1
	s_cmp_lg_u32 s11, 0
	s_cbranch_scc1 .Lgs3_poll
	s_branch .Lgs3_done
